# K-loop first-trip peel extended to all eight GEMM instances (w_in and GLU loops with rotating accumulators included)
# baseline (speedup 1.0000x reference)
; #define PG8_STAGE(bufoff, gbase, voff) do { _Pragma("unroll") for (int _i = 0; _i < 2; ++_i) \
;         __builtin_amdgcn_global_load_lds((const unsigned*)((const char*)(gbase) + (voff)[_i]), (LAS unsigned*)(lds + (bufoff) + ldsw + _i * 8192), 16, 0, 0); } while (0)
; #define PG8_LDA(dst, b, h) do { _Pragma("unroll") for (int m = 0; m < 4; ++m) _Pragma("unroll") for (int k = 0; k < 2; ++k) dst[m][k] = *(const LAS bf16x8*)(lds + PG8_SA(b, h) + aoff + m * 2048 + k * 1024); } while (0)
; #define PG8_LDB(dst, b, h) do { _Pragma("unroll") for (int n = 0; n < 2; ++n) _Pragma("unroll") for (int k = 0; k < 2; ++k) dst[n][k] = *(const LAS bf16x8*)(lds + PG8_SB(b, h) + boff + n * 2048 + k * 1024); } while (0)
; #define PG8_MMA(ai, bj, At, Bt) do { __builtin_amdgcn_s_setprio(1); _Pragma("unroll") for (int m = 0; m < 4; ++m) _Pragma("unroll") for (int n = 0; n < 2; ++n) _Pragma("unroll") for (int k = 0; k < 2; ++k) \
;         acc[ai][bj][m][n] = __builtin_amdgcn_mfma_f32_16x16x32_bf16(Bt[n][k], At[m][k], acc[ai][bj][m][n], 0, 0, 0); __builtin_amdgcn_s_setprio(0); } while (0)
; #define PG8_WAIT_V(n) asm volatile("s_waitcnt vmcnt(" #n ")" ::: "memory")
; #define PG8_WAIT_L(n) asm volatile("s_waitcnt lgkmcnt(" #n ")" ::: "memory")
; template <class Epi, class Sched, bool ALIGN_EPI, bool SP2, bool PERMA = false>
; __device__ __forceinline__ void gemm_phase(LAS unsigned char* lds, const int tid, const int lda, const int ldb, const Sched& S, const Epi& E) {
;     ...
;         const char* nA = has_next ? (const char*)nxt.A : cA; const char* nB = has_next ? (const char*)nxt.B : cB;
;         const int nt = cur.nt;
;         for (int t = 0; t < nt; t += 2) {
;             const bool last = (t == nt - 2);
;             const char* a1 = cA + (size_t)(t + 1) * kstep;
;             const char* a2 = last ? nA : cA + (size_t)(t + 2) * kstep; const char* b2 = last ? nB : cB + (size_t)(t + 2) * kstep;
;             const char* a3 = a2 + kstep; const char* b3 = b2 + kstep;
;             if constexpr (SP2) {
;             PG8_LDB(B0, 0, 0); PG8_LDB(B1, 0, 1); PG8_SCHED; PG8_LDA(At, 0, 0); PG8_STAGE(PG8_SA(1, 1), a1 + hsA, voffA);
;             PG8_WAIT_V(8); PG8_WAIT_L(0); PG8_BAR; PG8_MMA(0, 0, At, B0); PG8_MMA(0, 1, At, B1); PG8_BAR; PG8_SCHED;
;             PG8_LDA(At, 0, 1); PG8_STAGE(PG8_SB(0, 0), b2, voffB); PG8_STAGE(PG8_SB(0, 1), b2 + hsB, voffB); PG8_STAGE(PG8_SA(0, 0), a2, voffA);
.LBB0_383:
	s_add_u32 s2, s30, 0x100
	s_addc_u32 s3, s31, 0
	s_add_u32 s28, s28, 0x40080
	v_mov_b32_e32 v0, 0
	s_addc_u32 s29, s29, 0
	s_mov_b32 s13, -2
	s_waitcnt lgkmcnt(0)
	s_add_u32 s17, s28, 0xfffc0080
	s_addc_u32 s19, s29, -1
	s_add_i32 s21, 0, 0x10000
	s_cmp_eq_u32 s13, 4
	s_cselect_b32 s35, s25, s19
	s_cselect_b32 s34, s24, s17
	s_cselect_b32 s31, s27, s3
	s_cselect_b32 s30, s26, s2
	s_add_i32 s17, 0, 0x14000
	v_add_u32_e32 v60, s21, v174
	v_add_u32_e32 v166, s17, v174
	ds_read_b128 v[40:43], v60
	ds_read_b128 v[44:47], v60 offset:1024
	ds_read_b128 v[56:59], v60 offset:2048
	ds_read_b128 v[60:63], v60 offset:3072
	ds_read_b128 v[136:139], v166
	ds_read_b128 v[140:143], v166 offset:1024
	ds_read_b128 v[152:155], v166 offset:2048
	ds_read_b128 v[166:169], v166 offset:3072
	v_lshl_add_u64 v[170:171], s[28:29], 0, v[164:165]
	s_add_i32 m0, s95, 0xc000
	ds_read_b128 v[176:179], v175
	ds_read_b128 v[180:183], v175 offset:1024
	ds_read_b128 v[184:187], v175 offset:2048
	ds_read_b128 v[188:191], v175 offset:3072
	ds_read_b128 v[198:201], v175 offset:4096
	ds_read_b128 v[202:205], v175 offset:5120
	ds_read_b128 v[206:209], v175 offset:6144
	ds_read_b128 v[210:213], v175 offset:7168
	global_load_lds_dwordx4 v[170:171], off
	v_lshl_add_u64 v[170:171], s[28:29], 0, v[162:163]
	s_add_i32 m0, s95, 0xe000
	s_nop 0
	global_load_lds_dwordx4 v[170:171], off
	s_waitcnt vmcnt(8)
	s_waitcnt lgkmcnt(0)
	s_barrier
	s_setprio 1
	s_waitcnt lgkmcnt(0)
	v_mfma_f32_16x16x32_bf16 v[148:151], v[40:43], v[176:179], 0
	v_mfma_f32_16x16x32_bf16 v[144:147], v[56:59], v[176:179], 0
	v_mfma_f32_16x16x32_bf16 v[124:127], v[40:43], v[184:187], 0
	v_mfma_f32_16x16x32_bf16 v[120:123], v[56:59], v[184:187], 0
	v_mfma_f32_16x16x32_bf16 v[108:111], v[40:43], v[198:201], 0
	v_mfma_f32_16x16x32_bf16 v[104:107], v[56:59], v[198:201], 0
	v_mfma_f32_16x16x32_bf16 v[92:95], v[40:43], v[206:209], 0
	v_mfma_f32_16x16x32_bf16 v[88:91], v[56:59], v[206:209], 0
	v_mfma_f32_16x16x32_bf16 v[148:151], v[44:47], v[180:183], v[148:151]
	v_mfma_f32_16x16x32_bf16 v[144:147], v[60:63], v[180:183], v[144:147]
	v_mfma_f32_16x16x32_bf16 v[124:127], v[44:47], v[188:191], v[124:127]
	v_mfma_f32_16x16x32_bf16 v[120:123], v[60:63], v[188:191], v[120:123]
	v_mfma_f32_16x16x32_bf16 v[108:111], v[44:47], v[202:205], v[108:111]
	v_mfma_f32_16x16x32_bf16 v[104:107], v[60:63], v[202:205], v[104:107]
	v_mfma_f32_16x16x32_bf16 v[92:95], v[44:47], v[210:213], v[92:95]
	v_mfma_f32_16x16x32_bf16 v[88:91], v[60:63], v[210:213], v[88:91]
	s_setprio 0
	s_setprio 1
	v_mfma_f32_16x16x32_bf16 v[132:135], v[136:139], v[176:179], 0
	v_mfma_f32_16x16x32_bf16 v[128:131], v[152:155], v[176:179], 0
	v_mfma_f32_16x16x32_bf16 v[116:119], v[136:139], v[184:187], 0
	v_mfma_f32_16x16x32_bf16 v[112:115], v[152:155], v[184:187], 0
	v_mfma_f32_16x16x32_bf16 v[100:103], v[136:139], v[198:201], 0
	v_mfma_f32_16x16x32_bf16 v[96:99], v[152:155], v[198:201], 0
	v_mfma_f32_16x16x32_bf16 v[84:87], v[136:139], v[206:209], 0
	v_mfma_f32_16x16x32_bf16 v[80:83], v[152:155], v[206:209], 0
	v_mfma_f32_16x16x32_bf16 v[132:135], v[140:143], v[180:183], v[132:135]
	v_mfma_f32_16x16x32_bf16 v[128:131], v[166:169], v[180:183], v[128:131]
	v_mfma_f32_16x16x32_bf16 v[116:119], v[140:143], v[188:191], v[116:119]
	v_mfma_f32_16x16x32_bf16 v[112:115], v[166:169], v[188:191], v[112:115]
	v_mfma_f32_16x16x32_bf16 v[100:103], v[140:143], v[202:205], v[100:103]
	v_mfma_f32_16x16x32_bf16 v[96:99], v[166:169], v[202:205], v[96:99]
	v_mfma_f32_16x16x32_bf16 v[84:87], v[140:143], v[210:213], v[84:87]
	v_mfma_f32_16x16x32_bf16 v[80:83], v[166:169], v[210:213], v[80:83]
	s_setprio 0
	s_barrier
	s_add_i32 s19, s21, s94
	v_lshl_add_u64 v[170:171], s[30:31], 0, v[192:193]
	s_mov_b32 m0, s19
	ds_read_b128 v[176:179], v175 offset:16384
	ds_read_b128 v[180:183], v175 offset:17408
	ds_read_b128 v[184:187], v175 offset:18432
	ds_read_b128 v[188:191], v175 offset:19456
	ds_read_b128 v[198:201], v175 offset:20480
	ds_read_b128 v[202:205], v175 offset:21504
	ds_read_b128 v[206:209], v175 offset:22528
	ds_read_b128 v[210:213], v175 offset:23552
	global_load_lds_dwordx4 v[170:171], off
	s_add_i32 m0, s19, 0x2000
	s_add_u32 s60, s30, 0x20000
	v_lshl_add_u64 v[214:215], s[30:31], 0, v[156:157]
	s_addc_u32 s61, s31, 0
	s_add_i32 s17, s17, s94
	global_load_lds_dwordx4 v[214:215], off
	v_lshl_add_u64 v[216:217], s[60:61], 0, v[192:193]
	s_mov_b32 m0, s17
	v_lshl_add_u64 v[218:219], s[34:35], 0, v[158:159]
	global_load_lds_dwordx4 v[216:217], off
	v_lshl_add_u64 v[216:217], s[60:61], 0, v[156:157]
	s_add_i32 m0, s17, 0x2000
	s_nop 0
	global_load_lds_dwordx4 v[216:217], off
	v_lshl_add_u64 v[216:217], s[34:35], 0, v[160:161]
	s_mov_b32 m0, s95
	s_nop 0
	global_load_lds_dwordx4 v[216:217], off
	s_mov_b32 m0, s96
	s_nop 0
	global_load_lds_dwordx4 v[218:219], off
	s_waitcnt vmcnt(8)
	s_waitcnt lgkmcnt(0)
	s_barrier
; #define PG8_STAGE(bufoff, gbase, voff) do { _Pragma("unroll") for (int _i = 0; _i < 2; ++_i) \
;         __builtin_amdgcn_global_load_lds((const unsigned*)((const char*)(gbase) + (voff)[_i]), (LAS unsigned*)(lds + (bufoff) + ldsw + _i * 8192), 16, 0, 0); } while (0)
; #define PG8_LDA(dst, b, h) do { _Pragma("unroll") for (int m = 0; m < 4; ++m) _Pragma("unroll") for (int k = 0; k < 2; ++k) dst[m][k] = *(const LAS bf16x8*)(lds + PG8_SA(b, h) + aoff + m * 2048 + k * 1024); } while (0)
; #define PG8_LDB(dst, b, h) do { _Pragma("unroll") for (int n = 0; n < 2; ++n) _Pragma("unroll") for (int k = 0; k < 2; ++k) dst[n][k] = *(const LAS bf16x8*)(lds + PG8_SB(b, h) + boff + n * 2048 + k * 1024); } while (0)
; #define PG8_MMA(ai, bj, At, Bt) do { __builtin_amdgcn_s_setprio(1); _Pragma("unroll") for (int m = 0; m < 4; ++m) _Pragma("unroll") for (int n = 0; n < 2; ++n) _Pragma("unroll") for (int k = 0; k < 2; ++k) \
;         acc[ai][bj][m][n] = __builtin_amdgcn_mfma_f32_16x16x32_bf16(Bt[n][k], At[m][k], acc[ai][bj][m][n], 0, 0, 0); __builtin_amdgcn_s_setprio(0); } while (0)
; #define PG8_WAIT_V(n) asm volatile("s_waitcnt vmcnt(" #n ")" ::: "memory")
; #define PG8_WAIT_L(n) asm volatile("s_waitcnt lgkmcnt(" #n ")" ::: "memory")
; #define PG8_BAR __builtin_amdgcn_s_barrier()
; #define PG8_SCHED __builtin_amdgcn_sched_barrier(0)
; template <class Epi, class Sched, bool ALIGN_EPI, bool SP2, bool PERMA = false>
; __device__ __forceinline__ void gemm_phase(LAS unsigned char* lds, const int tid, const int lda, const int ldb, const Sched& S, const Epi& E) {
;     ...
;             PG8_WAIT_V(8); PG8_WAIT_L(0); PG8_BAR; PG8_MMA(1, 0, At, B0); PG8_MMA(1, 1, At, B1); PG8_BAR; PG8_SCHED;
;             PG8_LDB(B0, 1, 0); PG8_LDB(B1, 1, 1); PG8_SCHED; PG8_LDA(At, 1, 0); PG8_STAGE(PG8_SA(0, 1), a2 + hsA, voffA);
;             PG8_WAIT_V(8); PG8_WAIT_L(0); PG8_BAR; PG8_MMA(0, 0, At, B0); PG8_MMA(0, 1, At, B1); PG8_BAR; PG8_SCHED;
	s_setprio 1
	s_waitcnt lgkmcnt(0)
	v_mfma_f32_16x16x32_bf16 v[76:79], v[40:43], v[176:179], 0
	v_mfma_f32_16x16x32_bf16 v[72:75], v[56:59], v[176:179], 0
	v_mfma_f32_16x16x32_bf16 v[52:55], v[40:43], v[184:187], 0
	v_mfma_f32_16x16x32_bf16 v[48:51], v[56:59], v[184:187], 0
	v_mfma_f32_16x16x32_bf16 v[28:31], v[40:43], v[198:201], 0
	v_mfma_f32_16x16x32_bf16 v[24:27], v[56:59], v[198:201], 0
	v_mfma_f32_16x16x32_bf16 v[12:15], v[40:43], v[206:209], 0
	v_mfma_f32_16x16x32_bf16 v[8:11], v[56:59], v[206:209], 0
	v_mfma_f32_16x16x32_bf16 v[76:79], v[44:47], v[180:183], v[76:79]
	v_mfma_f32_16x16x32_bf16 v[72:75], v[60:63], v[180:183], v[72:75]
	v_mfma_f32_16x16x32_bf16 v[52:55], v[44:47], v[188:191], v[52:55]
	v_mfma_f32_16x16x32_bf16 v[48:51], v[60:63], v[188:191], v[48:51]
	v_mfma_f32_16x16x32_bf16 v[28:31], v[44:47], v[202:205], v[28:31]
	v_mfma_f32_16x16x32_bf16 v[24:27], v[60:63], v[202:205], v[24:27]
	v_mfma_f32_16x16x32_bf16 v[12:15], v[44:47], v[210:213], v[12:15]
	v_mfma_f32_16x16x32_bf16 v[8:11], v[60:63], v[210:213], v[8:11]
	s_setprio 0
	s_setprio 1
	v_mfma_f32_16x16x32_bf16 v[36:39], v[136:139], v[184:187], 0
	v_mfma_f32_16x16x32_bf16 v[32:35], v[152:155], v[184:187], 0
	v_mfma_f32_16x16x32_bf16 v[20:23], v[136:139], v[198:201], 0
	v_mfma_f32_16x16x32_bf16 v[16:19], v[152:155], v[198:201], 0
	v_mfma_f32_16x16x32_bf16 v[4:7], v[136:139], v[206:209], 0
	v_mfma_f32_16x16x32_bf16 v[0:3], v[152:155], v[206:209], 0
	v_mfma_f32_16x16x32_bf16 v[40:43], v[136:139], v[176:179], 0
	v_mfma_f32_16x16x32_bf16 v[44:47], v[152:155], v[176:179], 0
	v_mfma_f32_16x16x32_bf16 v[36:39], v[140:143], v[188:191], v[36:39]
	v_mfma_f32_16x16x32_bf16 v[32:35], v[166:169], v[188:191], v[32:35]
	v_mfma_f32_16x16x32_bf16 v[20:23], v[140:143], v[202:205], v[20:23]
	v_mfma_f32_16x16x32_bf16 v[16:19], v[166:169], v[202:205], v[16:19]
	v_mfma_f32_16x16x32_bf16 v[4:7], v[140:143], v[210:213], v[4:7]
	v_mfma_f32_16x16x32_bf16 v[0:3], v[166:169], v[210:213], v[0:3]
	v_mfma_f32_16x16x32_bf16 v[40:43], v[140:143], v[180:183], v[40:43]
	v_mfma_f32_16x16x32_bf16 v[44:47], v[166:169], v[180:183], v[44:47]
	s_setprio 0
	s_barrier
	s_add_i32 s17, 0, 0x18000
	s_add_i32 s19, 0, 0x1c000
	v_add_u32_e32 v68, s17, v174
	v_add_u32_e32 v166, s19, v174
	ds_read_b128 v[56:59], v68
	ds_read_b128 v[60:63], v68 offset:1024
	ds_read_b128 v[64:67], v68 offset:2048
	ds_read_b128 v[68:71], v68 offset:3072
	ds_read_b128 v[136:139], v166
	ds_read_b128 v[140:143], v166 offset:1024
	ds_read_b128 v[152:155], v166 offset:2048
	ds_read_b128 v[166:169], v166 offset:3072
	s_add_u32 s34, s34, 0x40000
	s_addc_u32 s35, s35, 0
	s_mov_b32 m0, s97
	v_lshl_add_u64 v[220:221], s[34:35], 0, v[160:161]
	ds_read_b128 v[176:179], v175 offset:32768
	ds_read_b128 v[180:183], v175 offset:33792
	ds_read_b128 v[184:187], v175 offset:34816
	ds_read_b128 v[188:191], v175 offset:35840
	ds_read_b128 v[198:201], v175 offset:36864
	ds_read_b128 v[202:205], v175 offset:37888
	ds_read_b128 v[206:209], v175 offset:38912
	ds_read_b128 v[210:213], v175 offset:39936
	global_load_lds_dwordx4 v[220:221], off
	v_lshl_add_u64 v[220:221], s[34:35], 0, v[158:159]
	s_mov_b32 m0, s6
	s_nop 0
	global_load_lds_dwordx4 v[220:221], off
	s_waitcnt vmcnt(8)
	s_waitcnt lgkmcnt(0)
	s_barrier
	s_setprio 1
	s_waitcnt lgkmcnt(0)
	v_mfma_f32_16x16x32_bf16 v[148:151], v[56:59], v[176:179], v[148:151]
	v_mfma_f32_16x16x32_bf16 v[144:147], v[64:67], v[176:179], v[144:147]
	v_mfma_f32_16x16x32_bf16 v[124:127], v[56:59], v[184:187], v[124:127]
	v_mfma_f32_16x16x32_bf16 v[120:123], v[64:67], v[184:187], v[120:123]
	v_mfma_f32_16x16x32_bf16 v[108:111], v[56:59], v[198:201], v[108:111]
	v_mfma_f32_16x16x32_bf16 v[104:107], v[64:67], v[198:201], v[104:107]
	v_mfma_f32_16x16x32_bf16 v[92:95], v[56:59], v[206:209], v[92:95]
	v_mfma_f32_16x16x32_bf16 v[88:91], v[64:67], v[206:209], v[88:91]
	v_mfma_f32_16x16x32_bf16 v[148:151], v[60:63], v[180:183], v[148:151]
	v_mfma_f32_16x16x32_bf16 v[144:147], v[68:71], v[180:183], v[144:147]
	v_mfma_f32_16x16x32_bf16 v[124:127], v[60:63], v[188:191], v[124:127]
	v_mfma_f32_16x16x32_bf16 v[120:123], v[68:71], v[188:191], v[120:123]
	v_mfma_f32_16x16x32_bf16 v[108:111], v[60:63], v[202:205], v[108:111]
	v_mfma_f32_16x16x32_bf16 v[104:107], v[68:71], v[202:205], v[104:107]
	v_mfma_f32_16x16x32_bf16 v[92:95], v[60:63], v[210:213], v[92:95]
	v_mfma_f32_16x16x32_bf16 v[88:91], v[68:71], v[210:213], v[88:91]
	s_setprio 0
	s_setprio 1
	v_mfma_f32_16x16x32_bf16 v[132:135], v[136:139], v[176:179], v[132:135]
	v_mfma_f32_16x16x32_bf16 v[128:131], v[152:155], v[176:179], v[128:131]
	v_mfma_f32_16x16x32_bf16 v[116:119], v[136:139], v[184:187], v[116:119]
	v_mfma_f32_16x16x32_bf16 v[112:115], v[152:155], v[184:187], v[112:115]
	v_mfma_f32_16x16x32_bf16 v[100:103], v[136:139], v[198:201], v[100:103]
	v_mfma_f32_16x16x32_bf16 v[96:99], v[152:155], v[198:201], v[96:99]
	v_mfma_f32_16x16x32_bf16 v[84:87], v[136:139], v[206:209], v[84:87]
	v_mfma_f32_16x16x32_bf16 v[80:83], v[152:155], v[206:209], v[80:83]
	v_mfma_f32_16x16x32_bf16 v[132:135], v[140:143], v[180:183], v[132:135]
	v_mfma_f32_16x16x32_bf16 v[128:131], v[166:169], v[180:183], v[128:131]
	v_mfma_f32_16x16x32_bf16 v[116:119], v[140:143], v[188:191], v[116:119]
	v_mfma_f32_16x16x32_bf16 v[112:115], v[166:169], v[188:191], v[112:115]
	v_mfma_f32_16x16x32_bf16 v[100:103], v[140:143], v[202:205], v[100:103]
	v_mfma_f32_16x16x32_bf16 v[96:99], v[166:169], v[202:205], v[96:99]
	v_mfma_f32_16x16x32_bf16 v[84:87], v[140:143], v[210:213], v[84:87]
	v_mfma_f32_16x16x32_bf16 v[80:83], v[166:169], v[210:213], v[80:83]
	s_setprio 0
	s_barrier
; #define PG8_STAGE(bufoff, gbase, voff) do { _Pragma("unroll") for (int _i = 0; _i < 2; ++_i) \
;         __builtin_amdgcn_global_load_lds((const unsigned*)((const char*)(gbase) + (voff)[_i]), (LAS unsigned*)(lds + (bufoff) + ldsw + _i * 8192), 16, 0, 0); } while (0)
; #define PG8_LDA(dst, b, h) do { _Pragma("unroll") for (int m = 0; m < 4; ++m) _Pragma("unroll") for (int k = 0; k < 2; ++k) dst[m][k] = *(const LAS bf16x8*)(lds + PG8_SA(b, h) + aoff + m * 2048 + k * 1024); } while (0)
; #define PG8_MMA(ai, bj, At, Bt) do { __builtin_amdgcn_s_setprio(1); _Pragma("unroll") for (int m = 0; m < 4; ++m) _Pragma("unroll") for (int n = 0; n < 2; ++n) _Pragma("unroll") for (int k = 0; k < 2; ++k) \
;         acc[ai][bj][m][n] = __builtin_amdgcn_mfma_f32_16x16x32_bf16(Bt[n][k], At[m][k], acc[ai][bj][m][n], 0, 0, 0); __builtin_amdgcn_s_setprio(0); } while (0)
; #define PG8_WAIT_V(n) asm volatile("s_waitcnt vmcnt(" #n ")" ::: "memory")
; #define PG8_WAIT_L(n) asm volatile("s_waitcnt lgkmcnt(" #n ")" ::: "memory")
; #define PG8_BAR __builtin_amdgcn_s_barrier()
; #define PG8_SCHED __builtin_amdgcn_sched_barrier(0)
; template <class Epi, class Sched, bool ALIGN_EPI, bool SP2, bool PERMA = false>
; __device__ __forceinline__ void gemm_phase(LAS unsigned char* lds, const int tid, const int lda, const int ldb, const Sched& S, const Epi& E) {
;     ...
;             PG8_LDA(At, 1, 1); PG8_STAGE(PG8_SB(1, 0), b3, voffB); PG8_STAGE(PG8_SB(1, 1), b3 + hsB, voffB); PG8_STAGE(PG8_SA(1, 0), a3, voffA);
;             PG8_WAIT_V(8); PG8_WAIT_L(0); PG8_BAR; PG8_MMA(1, 0, At, B0); PG8_MMA(1, 1, At, B1); PG8_BAR; PG8_SCHED;
	s_add_i32 s17, s17, s94
	v_lshl_add_u64 v[170:171], v[170:171], 0, s[54:55]
	s_mov_b32 m0, s17
	ds_read_b128 v[176:179], v175 offset:49152
	ds_read_b128 v[180:183], v175 offset:50176
	ds_read_b128 v[184:187], v175 offset:51200
	ds_read_b128 v[188:191], v175 offset:52224
	ds_read_b128 v[198:201], v175 offset:53248
	ds_read_b128 v[202:205], v175 offset:54272
	ds_read_b128 v[206:209], v175 offset:55296
	ds_read_b128 v[210:213], v175 offset:56320
	global_load_lds_dwordx4 v[170:171], off
	s_add_i32 m0, s17, 0x2000
	s_add_u32 s30, s30, 0x20080
	v_lshl_add_u64 v[170:171], v[214:215], 0, s[54:55]
	s_addc_u32 s31, s31, 0
	s_add_i32 s17, s19, s94
	global_load_lds_dwordx4 v[170:171], off
	v_lshl_add_u64 v[170:171], s[30:31], 0, v[192:193]
	s_mov_b32 m0, s17
	s_nop 0
	global_load_lds_dwordx4 v[170:171], off
	v_lshl_add_u64 v[170:171], s[30:31], 0, v[156:157]
	s_add_i32 m0, s17, 0x2000
	s_nop 0
	global_load_lds_dwordx4 v[170:171], off
	v_lshl_add_u64 v[170:171], v[216:217], 0, s[54:55]
	s_mov_b32 m0, s49
	s_nop 0
	global_load_lds_dwordx4 v[170:171], off
	v_lshl_add_u64 v[170:171], v[218:219], 0, s[54:55]
	s_mov_b32 m0, s51
	s_nop 0
	global_load_lds_dwordx4 v[170:171], off
	s_waitcnt vmcnt(8)
	s_waitcnt lgkmcnt(0)
	s_barrier
	s_setprio 1
	s_waitcnt lgkmcnt(0)
	v_mfma_f32_16x16x32_bf16 v[76:79], v[56:59], v[176:179], v[76:79]
	v_mfma_f32_16x16x32_bf16 v[72:75], v[64:67], v[176:179], v[72:75]
	v_mfma_f32_16x16x32_bf16 v[52:55], v[56:59], v[184:187], v[52:55]
	v_mfma_f32_16x16x32_bf16 v[48:51], v[64:67], v[184:187], v[48:51]
	v_mfma_f32_16x16x32_bf16 v[28:31], v[56:59], v[198:201], v[28:31]
	v_mfma_f32_16x16x32_bf16 v[24:27], v[64:67], v[198:201], v[24:27]
	v_mfma_f32_16x16x32_bf16 v[12:15], v[56:59], v[206:209], v[12:15]
	v_mfma_f32_16x16x32_bf16 v[8:11], v[64:67], v[206:209], v[8:11]
	v_mfma_f32_16x16x32_bf16 v[76:79], v[60:63], v[180:183], v[76:79]
	v_mfma_f32_16x16x32_bf16 v[72:75], v[68:71], v[180:183], v[72:75]
	v_mfma_f32_16x16x32_bf16 v[52:55], v[60:63], v[188:191], v[52:55]
	v_mfma_f32_16x16x32_bf16 v[48:51], v[68:71], v[188:191], v[48:51]
	v_mfma_f32_16x16x32_bf16 v[28:31], v[60:63], v[202:205], v[28:31]
	v_mfma_f32_16x16x32_bf16 v[24:27], v[68:71], v[202:205], v[24:27]
	v_mfma_f32_16x16x32_bf16 v[12:15], v[60:63], v[210:213], v[12:15]
	v_mfma_f32_16x16x32_bf16 v[8:11], v[68:71], v[210:213], v[8:11]
	s_setprio 0
	s_setprio 1
	v_mfma_f32_16x16x32_bf16 v[40:43], v[136:139], v[176:179], v[40:43]
	v_mfma_f32_16x16x32_bf16 v[68:71], v[140:143], v[180:183], v[40:43]
	v_mfma_f32_16x16x32_bf16 v[40:43], v[152:155], v[176:179], v[44:47]
	v_mfma_f32_16x16x32_bf16 v[36:39], v[136:139], v[184:187], v[36:39]
	v_mfma_f32_16x16x32_bf16 v[32:35], v[152:155], v[184:187], v[32:35]
	v_mfma_f32_16x16x32_bf16 v[20:23], v[136:139], v[198:201], v[20:23]
	v_mfma_f32_16x16x32_bf16 v[16:19], v[152:155], v[198:201], v[16:19]
	v_mfma_f32_16x16x32_bf16 v[4:7], v[136:139], v[206:209], v[4:7]
	v_mfma_f32_16x16x32_bf16 v[0:3], v[152:155], v[206:209], v[0:3]
	v_mfma_f32_16x16x32_bf16 v[64:67], v[166:169], v[180:183], v[40:43]
	v_mfma_f32_16x16x32_bf16 v[36:39], v[140:143], v[188:191], v[36:39]
	v_mfma_f32_16x16x32_bf16 v[32:35], v[166:169], v[188:191], v[32:35]
	v_mfma_f32_16x16x32_bf16 v[20:23], v[140:143], v[202:205], v[20:23]
	v_mfma_f32_16x16x32_bf16 v[16:19], v[166:169], v[202:205], v[16:19]
	v_mfma_f32_16x16x32_bf16 v[4:7], v[140:143], v[210:213], v[4:7]
	v_mfma_f32_16x16x32_bf16 v[0:3], v[166:169], v[210:213], v[0:3]
	s_setprio 0
	s_barrier
	s_add_i32 s13, s13, 2
	s_add_u32 s2, s2, 0x100
	s_addc_u32 s3, s3, 0
	s_add_u32 s28, s28, 0x100
	s_addc_u32 s29, s29, 0
	s_cmp_gt_u32 s13, 5
	s_cbranch_scc1 .Lgemm4_kdone

; #define PG8_BAR __builtin_amdgcn_s_barrier()
; template <class Epi, class Sched, bool ALIGN_EPI, bool SP2, bool PERMA = false>
; __device__ __forceinline__ void gemm_phase(LAS unsigned char* lds, const int tid, const int lda, const int ldb, const Sched& S, const Epi& E) {
;     ...
;         if constexpr (ALIGN_EPI) { if (wr == 0) PG8_BAR; }
.Lgemm4_kdone:
	v_readlane_b32 s2, v254, 44
	v_readlane_b32 s3, v254, 45
	s_and_b64 vcc, exec, s[2:3]
	s_cbranch_vccz .LBB0_387
	s_barrier

; #define PG8_STAGE(bufoff, gbase, voff) do { _Pragma("unroll") for (int _i = 0; _i < 2; ++_i) \
;         __builtin_amdgcn_global_load_lds((const unsigned*)((const char*)(gbase) + (voff)[_i]), (LAS unsigned*)(lds + (bufoff) + ldsw + _i * 8192), 16, 0, 0); } while (0)
; #define PG8_LDA(dst, b, h) do { _Pragma("unroll") for (int m = 0; m < 4; ++m) _Pragma("unroll") for (int k = 0; k < 2; ++k) dst[m][k] = *(const LAS bf16x8*)(lds + PG8_SA(b, h) + aoff + m * 2048 + k * 1024); } while (0)
; #define PG8_LDB(dst, b, h) do { _Pragma("unroll") for (int n = 0; n < 2; ++n) _Pragma("unroll") for (int k = 0; k < 2; ++k) dst[n][k] = *(const LAS bf16x8*)(lds + PG8_SB(b, h) + boff + n * 2048 + k * 1024); } while (0)
; #define PG8_MMA(ai, bj, At, Bt) do { __builtin_amdgcn_s_setprio(1); _Pragma("unroll") for (int m = 0; m < 4; ++m) _Pragma("unroll") for (int n = 0; n < 2; ++n) _Pragma("unroll") for (int k = 0; k < 2; ++k) \
;         acc[ai][bj][m][n] = __builtin_amdgcn_mfma_f32_16x16x32_bf16(Bt[n][k], At[m][k], acc[ai][bj][m][n], 0, 0, 0); __builtin_amdgcn_s_setprio(0); } while (0)
; #define PG8_WAIT_V(n) asm volatile("s_waitcnt vmcnt(" #n ")" ::: "memory")
; #define PG8_WAIT_L(n) asm volatile("s_waitcnt lgkmcnt(" #n ")" ::: "memory")
; template <class Epi, class Sched, bool ALIGN_EPI, bool SP2, bool PERMA = false>
; __device__ __forceinline__ void gemm_phase(LAS unsigned char* lds, const int tid, const int lda, const int ldb, const Sched& S, const Epi& E) {
;     ...
;         const char* nA = has_next ? (const char*)nxt.A : cA; const char* nB = has_next ? (const char*)nxt.B : cB;
;         const int nt = cur.nt;
;         for (int t = 0; t < nt; t += 2) {
;             const bool last = (t == nt - 2);
;             const char* a1 = cA + (size_t)(t + 1) * kstep;
;             const char* a2 = last ? nA : cA + (size_t)(t + 2) * kstep; const char* b2 = last ? nB : cB + (size_t)(t + 2) * kstep;
;             const char* a3 = a2 + kstep; const char* b3 = b2 + kstep;
;             if constexpr (SP2) {
;             PG8_LDB(B0, 0, 0); PG8_LDB(B1, 0, 1); PG8_SCHED; PG8_LDA(At, 0, 0); PG8_STAGE(PG8_SA(1, 1), a1 + hsA, voffA);
;             PG8_WAIT_V(8); PG8_WAIT_L(0); PG8_BAR; PG8_MMA(0, 0, At, B0); PG8_MMA(0, 1, At, B1); PG8_BAR; PG8_SCHED;
;             PG8_LDA(At, 0, 1); PG8_STAGE(PG8_SB(0, 0), b2, voffB); PG8_STAGE(PG8_SB(0, 1), b2 + hsB, voffB); PG8_STAGE(PG8_SA(0, 0), a2, voffA);
.LBB0_518:
	s_add_u32 s3, s16, 0x100
	s_addc_u32 s7, s17, 0
	s_add_u32 s8, s8, 0x40080
	v_mov_b32_e32 v0, 0
	s_addc_u32 s9, s9, 0
	s_mov_b32 s23, -2
	s_waitcnt vmcnt(0)
	s_waitcnt lgkmcnt(0)
	s_add_u32 s16, s8, 0xfffc0080
	s_addc_u32 s17, s9, -1
	s_add_i32 s24, 0, 0x10000
	s_cmp_eq_u32 s23, 12
	s_cselect_b32 s19, s21, s17
	s_cselect_b32 s18, s20, s16
	s_cselect_b32 s17, s95, s7
	s_cselect_b32 s16, s94, s3
	s_add_i32 s26, 0, 0x14000
	v_add_u32_e32 v60, s24, v207
	v_add_u32_e32 v156, s26, v207
	ds_read_b128 v[48:51], v60
	ds_read_b128 v[52:55], v60 offset:1024
	ds_read_b128 v[56:59], v60 offset:2048
	ds_read_b128 v[60:63], v60 offset:3072
	ds_read_b128 v[144:147], v156
	ds_read_b128 v[148:151], v156 offset:1024
	ds_read_b128 v[152:155], v156 offset:2048
	ds_read_b128 v[156:159], v156 offset:3072
	v_lshl_add_u64 v[210:211], s[8:9], 0, v[204:205]
	s_add_i32 m0, s0, 0xc000
	ds_read_b128 v[160:163], v208
	ds_read_b128 v[164:167], v208 offset:1024
	ds_read_b128 v[168:171], v208 offset:2048
	ds_read_b128 v[172:175], v208 offset:3072
	ds_read_b128 v[176:179], v208 offset:4096
	ds_read_b128 v[180:183], v208 offset:5120
	ds_read_b128 v[184:187], v208 offset:6144
	ds_read_b128 v[188:191], v208 offset:7168
	global_load_lds_dwordx4 v[210:211], off
	v_lshl_add_u64 v[210:211], s[8:9], 0, v[202:203]
	s_add_i32 m0, s0, 0xe000
	s_nop 0
	global_load_lds_dwordx4 v[210:211], off
	s_waitcnt vmcnt(8)
	s_waitcnt lgkmcnt(0)
	s_barrier
	s_setprio 1
	s_waitcnt lgkmcnt(0)
	v_mfma_f32_16x16x32_bf16 v[140:143], v[48:51], v[160:163], 0
	v_mfma_f32_16x16x32_bf16 v[136:139], v[56:59], v[160:163], 0
	v_mfma_f32_16x16x32_bf16 v[124:127], v[48:51], v[168:171], 0
	v_mfma_f32_16x16x32_bf16 v[120:123], v[56:59], v[168:171], 0
	v_mfma_f32_16x16x32_bf16 v[108:111], v[48:51], v[176:179], 0
	v_mfma_f32_16x16x32_bf16 v[104:107], v[56:59], v[176:179], 0
	v_mfma_f32_16x16x32_bf16 v[92:95], v[48:51], v[184:187], 0
	v_mfma_f32_16x16x32_bf16 v[88:91], v[56:59], v[184:187], 0
	v_mfma_f32_16x16x32_bf16 v[140:143], v[52:55], v[164:167], v[140:143]
	v_mfma_f32_16x16x32_bf16 v[136:139], v[60:63], v[164:167], v[136:139]
	v_mfma_f32_16x16x32_bf16 v[124:127], v[52:55], v[172:175], v[124:127]
	v_mfma_f32_16x16x32_bf16 v[120:123], v[60:63], v[172:175], v[120:123]
	v_mfma_f32_16x16x32_bf16 v[108:111], v[52:55], v[180:183], v[108:111]
	v_mfma_f32_16x16x32_bf16 v[104:107], v[60:63], v[180:183], v[104:107]
	v_mfma_f32_16x16x32_bf16 v[92:95], v[52:55], v[188:191], v[92:95]
	v_mfma_f32_16x16x32_bf16 v[88:91], v[60:63], v[188:191], v[88:91]
	s_setprio 0
	s_setprio 1
	v_mfma_f32_16x16x32_bf16 v[132:135], v[144:147], v[160:163], 0
	v_mfma_f32_16x16x32_bf16 v[128:131], v[152:155], v[160:163], 0
	v_mfma_f32_16x16x32_bf16 v[116:119], v[144:147], v[168:171], 0
	v_mfma_f32_16x16x32_bf16 v[112:115], v[152:155], v[168:171], 0
	v_mfma_f32_16x16x32_bf16 v[100:103], v[144:147], v[176:179], 0
	v_mfma_f32_16x16x32_bf16 v[96:99], v[152:155], v[176:179], 0
	v_mfma_f32_16x16x32_bf16 v[84:87], v[144:147], v[184:187], 0
	v_mfma_f32_16x16x32_bf16 v[80:83], v[152:155], v[184:187], 0
	v_mfma_f32_16x16x32_bf16 v[132:135], v[148:151], v[164:167], v[132:135]
	v_mfma_f32_16x16x32_bf16 v[128:131], v[156:159], v[164:167], v[128:131]
	v_mfma_f32_16x16x32_bf16 v[116:119], v[148:151], v[172:175], v[116:119]
	v_mfma_f32_16x16x32_bf16 v[112:115], v[156:159], v[172:175], v[112:115]
	v_mfma_f32_16x16x32_bf16 v[100:103], v[148:151], v[180:183], v[100:103]
	v_mfma_f32_16x16x32_bf16 v[96:99], v[156:159], v[180:183], v[96:99]
	v_mfma_f32_16x16x32_bf16 v[84:87], v[148:151], v[188:191], v[84:87]
	v_mfma_f32_16x16x32_bf16 v[80:83], v[156:159], v[188:191], v[80:83]
	s_setprio 0
	s_barrier
	s_add_i32 s24, s24, s92
	v_lshl_add_u64 v[210:211], s[16:17], 0, v[198:199]
	s_mov_b32 m0, s24
	ds_read_b128 v[160:163], v208 offset:16384
	ds_read_b128 v[164:167], v208 offset:17408
	ds_read_b128 v[168:171], v208 offset:18432
	ds_read_b128 v[172:175], v208 offset:19456
	ds_read_b128 v[176:179], v208 offset:20480
	ds_read_b128 v[180:183], v208 offset:21504
	ds_read_b128 v[184:187], v208 offset:22528
	ds_read_b128 v[188:191], v208 offset:23552
	global_load_lds_dwordx4 v[210:211], off
	s_add_i32 m0, s24, 0x2000
	s_add_u32 s24, s16, 0x40000
	v_lshl_add_u64 v[212:213], s[16:17], 0, v[200:201]
	s_addc_u32 s25, s17, 0
	s_add_i32 s26, s26, s92
	global_load_lds_dwordx4 v[212:213], off
	v_lshl_add_u64 v[214:215], s[24:25], 0, v[198:199]
	s_mov_b32 m0, s26
	v_lshl_add_u64 v[216:217], s[18:19], 0, v[200:201]
	global_load_lds_dwordx4 v[214:215], off
	v_lshl_add_u64 v[214:215], s[24:25], 0, v[200:201]
	s_add_i32 m0, s26, 0x2000
	s_nop 0
	global_load_lds_dwordx4 v[214:215], off
	v_lshl_add_u64 v[214:215], s[18:19], 0, v[198:199]
	s_mov_b32 m0, s0
	s_nop 0
	global_load_lds_dwordx4 v[214:215], off
	s_mov_b32 m0, s1
	s_nop 0
	global_load_lds_dwordx4 v[216:217], off
	s_waitcnt vmcnt(8)
	s_waitcnt lgkmcnt(0)
	s_barrier
; #define PG8_STAGE(bufoff, gbase, voff) do { _Pragma("unroll") for (int _i = 0; _i < 2; ++_i) \
;         __builtin_amdgcn_global_load_lds((const unsigned*)((const char*)(gbase) + (voff)[_i]), (LAS unsigned*)(lds + (bufoff) + ldsw + _i * 8192), 16, 0, 0); } while (0)
; #define PG8_LDA(dst, b, h) do { _Pragma("unroll") for (int m = 0; m < 4; ++m) _Pragma("unroll") for (int k = 0; k < 2; ++k) dst[m][k] = *(const LAS bf16x8*)(lds + PG8_SA(b, h) + aoff + m * 2048 + k * 1024); } while (0)
; #define PG8_LDB(dst, b, h) do { _Pragma("unroll") for (int n = 0; n < 2; ++n) _Pragma("unroll") for (int k = 0; k < 2; ++k) dst[n][k] = *(const LAS bf16x8*)(lds + PG8_SB(b, h) + boff + n * 2048 + k * 1024); } while (0)
; #define PG8_MMA(ai, bj, At, Bt) do { __builtin_amdgcn_s_setprio(1); _Pragma("unroll") for (int m = 0; m < 4; ++m) _Pragma("unroll") for (int n = 0; n < 2; ++n) _Pragma("unroll") for (int k = 0; k < 2; ++k) \
;         acc[ai][bj][m][n] = __builtin_amdgcn_mfma_f32_16x16x32_bf16(Bt[n][k], At[m][k], acc[ai][bj][m][n], 0, 0, 0); __builtin_amdgcn_s_setprio(0); } while (0)
; #define PG8_WAIT_V(n) asm volatile("s_waitcnt vmcnt(" #n ")" ::: "memory")
; #define PG8_WAIT_L(n) asm volatile("s_waitcnt lgkmcnt(" #n ")" ::: "memory")
; #define PG8_BAR __builtin_amdgcn_s_barrier()
; #define PG8_SCHED __builtin_amdgcn_sched_barrier(0)
; template <class Epi, class Sched, bool ALIGN_EPI, bool SP2, bool PERMA = false>
; __device__ __forceinline__ void gemm_phase(LAS unsigned char* lds, const int tid, const int lda, const int ldb, const Sched& S, const Epi& E) {
;     ...
;             PG8_WAIT_V(8); PG8_WAIT_L(0); PG8_BAR; PG8_MMA(1, 0, At, B0); PG8_MMA(1, 1, At, B1); PG8_BAR; PG8_SCHED;
;             PG8_LDB(B0, 1, 0); PG8_LDB(B1, 1, 1); PG8_SCHED; PG8_LDA(At, 1, 0); PG8_STAGE(PG8_SA(0, 1), a2 + hsA, voffA);
;             PG8_WAIT_V(8); PG8_WAIT_L(0); PG8_BAR; PG8_MMA(0, 0, At, B0); PG8_MMA(0, 1, At, B1); PG8_BAR; PG8_SCHED;
	s_setprio 1
	s_waitcnt lgkmcnt(0)
	v_mfma_f32_16x16x32_bf16 v[76:79], v[48:51], v[160:163], 0
	v_mfma_f32_16x16x32_bf16 v[72:75], v[56:59], v[160:163], 0
	v_mfma_f32_16x16x32_bf16 v[44:47], v[48:51], v[168:171], 0
	v_mfma_f32_16x16x32_bf16 v[40:43], v[56:59], v[168:171], 0
	v_mfma_f32_16x16x32_bf16 v[28:31], v[48:51], v[176:179], 0
	v_mfma_f32_16x16x32_bf16 v[24:27], v[56:59], v[176:179], 0
	v_mfma_f32_16x16x32_bf16 v[12:15], v[48:51], v[184:187], 0
	v_mfma_f32_16x16x32_bf16 v[8:11], v[56:59], v[184:187], 0
	v_mfma_f32_16x16x32_bf16 v[76:79], v[52:55], v[164:167], v[76:79]
	v_mfma_f32_16x16x32_bf16 v[72:75], v[60:63], v[164:167], v[72:75]
	v_mfma_f32_16x16x32_bf16 v[44:47], v[52:55], v[172:175], v[44:47]
	v_mfma_f32_16x16x32_bf16 v[40:43], v[60:63], v[172:175], v[40:43]
	v_mfma_f32_16x16x32_bf16 v[28:31], v[52:55], v[180:183], v[28:31]
	v_mfma_f32_16x16x32_bf16 v[24:27], v[60:63], v[180:183], v[24:27]
	v_mfma_f32_16x16x32_bf16 v[12:15], v[52:55], v[188:191], v[12:15]
	v_mfma_f32_16x16x32_bf16 v[8:11], v[60:63], v[188:191], v[8:11]
	s_setprio 0
	s_setprio 1
	v_mfma_f32_16x16x32_bf16 v[36:39], v[144:147], v[168:171], 0
	v_mfma_f32_16x16x32_bf16 v[32:35], v[152:155], v[168:171], 0
	v_mfma_f32_16x16x32_bf16 v[20:23], v[144:147], v[176:179], 0
	v_mfma_f32_16x16x32_bf16 v[16:19], v[152:155], v[176:179], 0
	v_mfma_f32_16x16x32_bf16 v[4:7], v[144:147], v[184:187], 0
	v_mfma_f32_16x16x32_bf16 v[0:3], v[152:155], v[184:187], 0
	v_mfma_f32_16x16x32_bf16 v[48:51], v[144:147], v[160:163], 0
	v_mfma_f32_16x16x32_bf16 v[52:55], v[152:155], v[160:163], 0
	v_mfma_f32_16x16x32_bf16 v[36:39], v[148:151], v[172:175], v[36:39]
	v_mfma_f32_16x16x32_bf16 v[32:35], v[156:159], v[172:175], v[32:35]
	v_mfma_f32_16x16x32_bf16 v[20:23], v[148:151], v[180:183], v[20:23]
	v_mfma_f32_16x16x32_bf16 v[16:19], v[156:159], v[180:183], v[16:19]
	v_mfma_f32_16x16x32_bf16 v[4:7], v[148:151], v[188:191], v[4:7]
	v_mfma_f32_16x16x32_bf16 v[0:3], v[156:159], v[188:191], v[0:3]
	v_mfma_f32_16x16x32_bf16 v[48:51], v[148:151], v[164:167], v[48:51]
	v_mfma_f32_16x16x32_bf16 v[52:55], v[156:159], v[164:167], v[52:55]
	s_setprio 0
	s_barrier
	s_add_i32 s24, 0, 0x18000
	s_add_i32 s25, 0, 0x1c000
	v_add_u32_e32 v68, s24, v207
	v_add_u32_e32 v156, s25, v207
	ds_read_b128 v[56:59], v68
	ds_read_b128 v[60:63], v68 offset:1024
	ds_read_b128 v[64:67], v68 offset:2048
	ds_read_b128 v[68:71], v68 offset:3072
	ds_read_b128 v[144:147], v156
	ds_read_b128 v[148:151], v156 offset:1024
	ds_read_b128 v[152:155], v156 offset:2048
	ds_read_b128 v[156:159], v156 offset:3072
	s_add_u32 s18, s18, 0x40000
	s_addc_u32 s19, s19, 0
	s_mov_b32 m0, s34
	v_lshl_add_u64 v[218:219], s[18:19], 0, v[198:199]
	ds_read_b128 v[160:163], v208 offset:32768
	ds_read_b128 v[164:167], v208 offset:33792
	ds_read_b128 v[168:171], v208 offset:34816
	ds_read_b128 v[172:175], v208 offset:35840
	ds_read_b128 v[176:179], v208 offset:36864
	ds_read_b128 v[180:183], v208 offset:37888
	ds_read_b128 v[184:187], v208 offset:38912
	ds_read_b128 v[188:191], v208 offset:39936
	global_load_lds_dwordx4 v[218:219], off
	v_lshl_add_u64 v[218:219], s[18:19], 0, v[200:201]
	s_mov_b32 m0, s35
	s_nop 0
	global_load_lds_dwordx4 v[218:219], off
	s_waitcnt vmcnt(8)
	s_waitcnt lgkmcnt(0)
	s_barrier
	s_setprio 1
	s_waitcnt lgkmcnt(0)
	v_mfma_f32_16x16x32_bf16 v[140:143], v[56:59], v[160:163], v[140:143]
	v_mfma_f32_16x16x32_bf16 v[136:139], v[64:67], v[160:163], v[136:139]
	v_mfma_f32_16x16x32_bf16 v[124:127], v[56:59], v[168:171], v[124:127]
	v_mfma_f32_16x16x32_bf16 v[120:123], v[64:67], v[168:171], v[120:123]
	v_mfma_f32_16x16x32_bf16 v[108:111], v[56:59], v[176:179], v[108:111]
	v_mfma_f32_16x16x32_bf16 v[104:107], v[64:67], v[176:179], v[104:107]
	v_mfma_f32_16x16x32_bf16 v[92:95], v[56:59], v[184:187], v[92:95]
	v_mfma_f32_16x16x32_bf16 v[88:91], v[64:67], v[184:187], v[88:91]
	v_mfma_f32_16x16x32_bf16 v[140:143], v[60:63], v[164:167], v[140:143]
	v_mfma_f32_16x16x32_bf16 v[136:139], v[68:71], v[164:167], v[136:139]
	v_mfma_f32_16x16x32_bf16 v[124:127], v[60:63], v[172:175], v[124:127]
	v_mfma_f32_16x16x32_bf16 v[120:123], v[68:71], v[172:175], v[120:123]
	v_mfma_f32_16x16x32_bf16 v[108:111], v[60:63], v[180:183], v[108:111]
	v_mfma_f32_16x16x32_bf16 v[104:107], v[68:71], v[180:183], v[104:107]
	v_mfma_f32_16x16x32_bf16 v[92:95], v[60:63], v[188:191], v[92:95]
	v_mfma_f32_16x16x32_bf16 v[88:91], v[68:71], v[188:191], v[88:91]
	s_setprio 0
	s_setprio 1
	v_mfma_f32_16x16x32_bf16 v[132:135], v[144:147], v[160:163], v[132:135]
	v_mfma_f32_16x16x32_bf16 v[128:131], v[152:155], v[160:163], v[128:131]
	v_mfma_f32_16x16x32_bf16 v[116:119], v[144:147], v[168:171], v[116:119]
	v_mfma_f32_16x16x32_bf16 v[112:115], v[152:155], v[168:171], v[112:115]
	v_mfma_f32_16x16x32_bf16 v[100:103], v[144:147], v[176:179], v[100:103]
	v_mfma_f32_16x16x32_bf16 v[96:99], v[152:155], v[176:179], v[96:99]
	v_mfma_f32_16x16x32_bf16 v[84:87], v[144:147], v[184:187], v[84:87]
	v_mfma_f32_16x16x32_bf16 v[80:83], v[152:155], v[184:187], v[80:83]
	v_mfma_f32_16x16x32_bf16 v[132:135], v[148:151], v[164:167], v[132:135]
	v_mfma_f32_16x16x32_bf16 v[128:131], v[156:159], v[164:167], v[128:131]
	v_mfma_f32_16x16x32_bf16 v[116:119], v[148:151], v[172:175], v[116:119]
	v_mfma_f32_16x16x32_bf16 v[112:115], v[156:159], v[172:175], v[112:115]
	v_mfma_f32_16x16x32_bf16 v[100:103], v[148:151], v[180:183], v[100:103]
	v_mfma_f32_16x16x32_bf16 v[96:99], v[156:159], v[180:183], v[96:99]
	v_mfma_f32_16x16x32_bf16 v[84:87], v[148:151], v[188:191], v[84:87]
	v_mfma_f32_16x16x32_bf16 v[80:83], v[156:159], v[188:191], v[80:83]
	s_setprio 0
	s_barrier
; #define PG8_STAGE(bufoff, gbase, voff) do { _Pragma("unroll") for (int _i = 0; _i < 2; ++_i) \
;         __builtin_amdgcn_global_load_lds((const unsigned*)((const char*)(gbase) + (voff)[_i]), (LAS unsigned*)(lds + (bufoff) + ldsw + _i * 8192), 16, 0, 0); } while (0)
; #define PG8_LDA(dst, b, h) do { _Pragma("unroll") for (int m = 0; m < 4; ++m) _Pragma("unroll") for (int k = 0; k < 2; ++k) dst[m][k] = *(const LAS bf16x8*)(lds + PG8_SA(b, h) + aoff + m * 2048 + k * 1024); } while (0)
; #define PG8_MMA(ai, bj, At, Bt) do { __builtin_amdgcn_s_setprio(1); _Pragma("unroll") for (int m = 0; m < 4; ++m) _Pragma("unroll") for (int n = 0; n < 2; ++n) _Pragma("unroll") for (int k = 0; k < 2; ++k) \
;         acc[ai][bj][m][n] = __builtin_amdgcn_mfma_f32_16x16x32_bf16(Bt[n][k], At[m][k], acc[ai][bj][m][n], 0, 0, 0); __builtin_amdgcn_s_setprio(0); } while (0)
; #define PG8_WAIT_V(n) asm volatile("s_waitcnt vmcnt(" #n ")" ::: "memory")
; #define PG8_WAIT_L(n) asm volatile("s_waitcnt lgkmcnt(" #n ")" ::: "memory")
; #define PG8_BAR __builtin_amdgcn_s_barrier()
; #define PG8_SCHED __builtin_amdgcn_sched_barrier(0)
; template <class Epi, class Sched, bool ALIGN_EPI, bool SP2, bool PERMA = false>
; __device__ __forceinline__ void gemm_phase(LAS unsigned char* lds, const int tid, const int lda, const int ldb, const Sched& S, const Epi& E) {
;     ...
;             PG8_LDA(At, 1, 1); PG8_STAGE(PG8_SB(1, 0), b3, voffB); PG8_STAGE(PG8_SB(1, 1), b3 + hsB, voffB); PG8_STAGE(PG8_SA(1, 0), a3, voffA);
;             PG8_WAIT_V(8); PG8_WAIT_L(0); PG8_BAR; PG8_MMA(1, 0, At, B0); PG8_MMA(1, 1, At, B1); PG8_BAR; PG8_SCHED;
	s_add_i32 s18, s24, s92
	v_lshl_add_u64 v[210:211], v[210:211], 0, s[54:55]
	s_mov_b32 m0, s18
	ds_read_b128 v[160:163], v208 offset:49152
	ds_read_b128 v[164:167], v208 offset:50176
	ds_read_b128 v[168:171], v208 offset:51200
	ds_read_b128 v[172:175], v208 offset:52224
	ds_read_b128 v[176:179], v208 offset:53248
	ds_read_b128 v[180:183], v208 offset:54272
	ds_read_b128 v[184:187], v208 offset:55296
	ds_read_b128 v[188:191], v208 offset:56320
	global_load_lds_dwordx4 v[210:211], off
	s_add_i32 m0, s18, 0x2000
	s_add_u32 s16, s16, 0x40080
	v_lshl_add_u64 v[210:211], v[212:213], 0, s[54:55]
	s_addc_u32 s17, s17, 0
	s_add_i32 s18, s25, s92
	global_load_lds_dwordx4 v[210:211], off
	v_lshl_add_u64 v[210:211], s[16:17], 0, v[198:199]
	s_mov_b32 m0, s18
	s_nop 0
	global_load_lds_dwordx4 v[210:211], off
	v_lshl_add_u64 v[210:211], s[16:17], 0, v[200:201]
	s_add_i32 m0, s18, 0x2000
	s_nop 0
	global_load_lds_dwordx4 v[210:211], off
	v_lshl_add_u64 v[210:211], v[214:215], 0, s[54:55]
	s_mov_b32 m0, s51
	s_nop 0
	global_load_lds_dwordx4 v[210:211], off
	v_lshl_add_u64 v[210:211], v[216:217], 0, s[54:55]
	s_mov_b32 m0, s49
	s_nop 0
	global_load_lds_dwordx4 v[210:211], off
	s_waitcnt vmcnt(8)
	s_waitcnt lgkmcnt(0)
	s_barrier
	s_setprio 1
	s_waitcnt lgkmcnt(0)
	v_mfma_f32_16x16x32_bf16 v[76:79], v[56:59], v[160:163], v[76:79]
	v_mfma_f32_16x16x32_bf16 v[72:75], v[64:67], v[160:163], v[72:75]
	v_mfma_f32_16x16x32_bf16 v[44:47], v[56:59], v[168:171], v[44:47]
	v_mfma_f32_16x16x32_bf16 v[40:43], v[64:67], v[168:171], v[40:43]
	v_mfma_f32_16x16x32_bf16 v[28:31], v[56:59], v[176:179], v[28:31]
	v_mfma_f32_16x16x32_bf16 v[24:27], v[64:67], v[176:179], v[24:27]
	v_mfma_f32_16x16x32_bf16 v[12:15], v[56:59], v[184:187], v[12:15]
	v_mfma_f32_16x16x32_bf16 v[8:11], v[64:67], v[184:187], v[8:11]
	v_mfma_f32_16x16x32_bf16 v[76:79], v[60:63], v[164:167], v[76:79]
	v_mfma_f32_16x16x32_bf16 v[72:75], v[68:71], v[164:167], v[72:75]
	v_mfma_f32_16x16x32_bf16 v[44:47], v[60:63], v[172:175], v[44:47]
	v_mfma_f32_16x16x32_bf16 v[40:43], v[68:71], v[172:175], v[40:43]
	v_mfma_f32_16x16x32_bf16 v[28:31], v[60:63], v[180:183], v[28:31]
	v_mfma_f32_16x16x32_bf16 v[24:27], v[68:71], v[180:183], v[24:27]
	v_mfma_f32_16x16x32_bf16 v[12:15], v[60:63], v[188:191], v[12:15]
	v_mfma_f32_16x16x32_bf16 v[8:11], v[68:71], v[188:191], v[8:11]
	s_setprio 0
	s_setprio 1
	v_mfma_f32_16x16x32_bf16 v[48:51], v[144:147], v[160:163], v[48:51]
	v_mfma_f32_16x16x32_bf16 v[68:71], v[148:151], v[164:167], v[48:51]
	v_mfma_f32_16x16x32_bf16 v[48:51], v[152:155], v[160:163], v[52:55]
	v_mfma_f32_16x16x32_bf16 v[36:39], v[144:147], v[168:171], v[36:39]
	v_mfma_f32_16x16x32_bf16 v[32:35], v[152:155], v[168:171], v[32:35]
	v_mfma_f32_16x16x32_bf16 v[20:23], v[144:147], v[176:179], v[20:23]
	v_mfma_f32_16x16x32_bf16 v[16:19], v[152:155], v[176:179], v[16:19]
	v_mfma_f32_16x16x32_bf16 v[4:7], v[144:147], v[184:187], v[4:7]
	v_mfma_f32_16x16x32_bf16 v[0:3], v[152:155], v[184:187], v[0:3]
	v_mfma_f32_16x16x32_bf16 v[64:67], v[156:159], v[164:167], v[48:51]
	v_mfma_f32_16x16x32_bf16 v[36:39], v[148:151], v[172:175], v[36:39]
	v_mfma_f32_16x16x32_bf16 v[32:35], v[156:159], v[172:175], v[32:35]
	v_mfma_f32_16x16x32_bf16 v[20:23], v[148:151], v[180:183], v[20:23]
	v_mfma_f32_16x16x32_bf16 v[16:19], v[156:159], v[180:183], v[16:19]
	v_mfma_f32_16x16x32_bf16 v[4:7], v[148:151], v[188:191], v[4:7]
	v_mfma_f32_16x16x32_bf16 v[0:3], v[156:159], v[188:191], v[0:3]
	s_setprio 0
	s_barrier
	s_add_i32 s23, s23, 2
	s_add_u32 s3, s3, 0x100
	s_addc_u32 s7, s7, 0
	s_add_u32 s8, s8, 0x100
	s_addc_u32 s9, s9, 0
	s_cmp_gt_u32 s23, 13
	s_cbranch_scc1 .Lgemm7_kdone

; #define PG8_BAR __builtin_amdgcn_s_barrier()
; template <class Epi, class Sched, bool ALIGN_EPI, bool SP2, bool PERMA = false>
; __device__ __forceinline__ void gemm_phase(LAS unsigned char* lds, const int tid, const int lda, const int ldb, const Sched& S, const Epi& E) {
;     ...
;         if constexpr (ALIGN_EPI) { if (wr == 0) PG8_BAR; }
.Lgemm7_kdone:
	v_readlane_b32 s8, v254, 42
	v_readlane_b32 s9, v254, 43
	s_and_b64 vcc, exec, s[8:9]
	s_cbranch_vccz .LBB0_522
	s_barrier
